# GEMM1 epilogue: per-tile bias loads issued at the K-loop exit, ahead of the conditional alignment barrier and the activation-select scalar code
# speedup vs baseline: 1.0100x; 1.0100x over previous
.LBB0_258:
	s_add_u32 s46, s44, 0xfff80080
	s_addc_u32 s47, s45, -1
	s_add_i32 s59, 0, 0x10000
	s_cmp_eq_u32 s58, 28
	s_cselect_b32 s49, s19, s47
	s_cselect_b32 s48, s20, s46
	s_cselect_b32 s47, s21, s57
	s_cselect_b32 s46, s23, s29
	s_add_i32 s62, 0, 0x14000
	v_add_u32_e32 v46, s59, v163
	v_add_u32_e32 v160, s62, v163
	ds_read_b128 v[26:29], v46
	ds_read_b128 v[30:33], v46 offset:1024
	ds_read_b128 v[42:45], v46 offset:2048
	ds_read_b128 v[46:49], v46 offset:3072
	ds_read_b128 v[166:169], v160
	ds_read_b128 v[178:181], v160 offset:1024
	ds_read_b128 v[182:185], v160 offset:2048
	ds_read_b128 v[186:189], v160 offset:3072
	v_lshl_add_u64 v[160:161], s[44:45], 0, v[156:157]
	s_add_i32 m0, s43, 0xc000
	ds_read_b128 v[190:193], v165
	ds_read_b128 v[194:197], v165 offset:1024
	ds_read_b128 v[204:207], v165 offset:2048
	ds_read_b128 v[208:211], v165 offset:3072
	ds_read_b128 v[212:215], v165 offset:4096
	ds_read_b128 v[216:219], v165 offset:5120
	ds_read_b128 v[220:223], v165 offset:6144
	ds_read_b128 v[224:227], v165 offset:7168
	global_load_lds_dwordx4 v[160:161], off
	v_lshl_add_u64 v[160:161], s[44:45], 0, v[158:159]
	s_add_i32 m0, s43, 0xe000
	s_nop 0
	global_load_lds_dwordx4 v[160:161], off
	s_waitcnt vmcnt(8)
	s_waitcnt lgkmcnt(0)
	s_barrier
	s_setprio 1
	s_waitcnt lgkmcnt(0)
	v_mfma_f32_16x16x32_bf16 v[146:149], v[26:29], v[190:193], v[146:149]
	v_mfma_f32_16x16x32_bf16 v[142:145], v[42:45], v[190:193], v[142:145]
	v_mfma_f32_16x16x32_bf16 v[130:133], v[26:29], v[204:207], v[130:133]
	v_mfma_f32_16x16x32_bf16 v[126:129], v[42:45], v[204:207], v[126:129]
	v_mfma_f32_16x16x32_bf16 v[114:117], v[26:29], v[212:215], v[114:117]
	v_mfma_f32_16x16x32_bf16 v[110:113], v[42:45], v[212:215], v[110:113]
	v_mfma_f32_16x16x32_bf16 v[94:97], v[26:29], v[220:223], v[94:97]
	v_mfma_f32_16x16x32_bf16 v[90:93], v[42:45], v[220:223], v[90:93]
	v_mfma_f32_16x16x32_bf16 v[146:149], v[30:33], v[194:197], v[146:149]
	v_mfma_f32_16x16x32_bf16 v[142:145], v[46:49], v[194:197], v[142:145]
	v_mfma_f32_16x16x32_bf16 v[130:133], v[30:33], v[208:211], v[130:133]
	v_mfma_f32_16x16x32_bf16 v[126:129], v[46:49], v[208:211], v[126:129]
	v_mfma_f32_16x16x32_bf16 v[114:117], v[30:33], v[216:219], v[114:117]
	v_mfma_f32_16x16x32_bf16 v[110:113], v[46:49], v[216:219], v[110:113]
	v_mfma_f32_16x16x32_bf16 v[94:97], v[30:33], v[224:227], v[94:97]
	v_mfma_f32_16x16x32_bf16 v[90:93], v[46:49], v[224:227], v[90:93]
	s_setprio 0
	s_setprio 1
	v_mfma_f32_16x16x32_bf16 v[138:141], v[166:169], v[190:193], v[138:141]
	v_mfma_f32_16x16x32_bf16 v[134:137], v[182:185], v[190:193], v[134:137]
	v_mfma_f32_16x16x32_bf16 v[122:125], v[166:169], v[204:207], v[122:125]
	v_mfma_f32_16x16x32_bf16 v[118:121], v[182:185], v[204:207], v[118:121]
	v_mfma_f32_16x16x32_bf16 v[106:109], v[166:169], v[212:215], v[106:109]
	v_mfma_f32_16x16x32_bf16 v[102:105], v[182:185], v[212:215], v[102:105]
	v_mfma_f32_16x16x32_bf16 v[86:89], v[166:169], v[220:223], v[86:89]
	v_mfma_f32_16x16x32_bf16 v[82:85], v[182:185], v[220:223], v[82:85]
	v_mfma_f32_16x16x32_bf16 v[138:141], v[178:181], v[194:197], v[138:141]
	v_mfma_f32_16x16x32_bf16 v[134:137], v[186:189], v[194:197], v[134:137]
	v_mfma_f32_16x16x32_bf16 v[122:125], v[178:181], v[208:211], v[122:125]
	v_mfma_f32_16x16x32_bf16 v[118:121], v[186:189], v[208:211], v[118:121]
	v_mfma_f32_16x16x32_bf16 v[106:109], v[178:181], v[216:219], v[106:109]
	v_mfma_f32_16x16x32_bf16 v[102:105], v[186:189], v[216:219], v[102:105]
	v_mfma_f32_16x16x32_bf16 v[86:89], v[178:181], v[224:227], v[86:89]
	v_mfma_f32_16x16x32_bf16 v[82:85], v[186:189], v[224:227], v[82:85]
	s_setprio 0
	s_barrier
	s_add_i32 s59, s59, s50
	v_lshl_add_u64 v[160:161], s[46:47], 0, v[172:173]
	s_mov_b32 m0, s59
	ds_read_b128 v[190:193], v165 offset:16384
	ds_read_b128 v[194:197], v165 offset:17408
	ds_read_b128 v[204:207], v165 offset:18432
	ds_read_b128 v[208:211], v165 offset:19456
	ds_read_b128 v[212:215], v165 offset:20480
	ds_read_b128 v[216:219], v165 offset:21504
	ds_read_b128 v[220:223], v165 offset:22528
	ds_read_b128 v[224:227], v165 offset:23552
	global_load_lds_dwordx4 v[160:161], off
	s_add_i32 m0, s59, 0x2000
	s_add_u32 s60, s46, 0x80000
	v_lshl_add_u64 v[198:199], s[46:47], 0, v[154:155]
	s_addc_u32 s61, s47, 0
	s_add_i32 s59, s62, s50
	global_load_lds_dwordx4 v[198:199], off
	v_lshl_add_u64 v[228:229], s[60:61], 0, v[172:173]
	s_mov_b32 m0, s59
	v_lshl_add_u64 v[230:231], s[48:49], 0, v[152:153]
	global_load_lds_dwordx4 v[228:229], off
	v_lshl_add_u64 v[228:229], s[60:61], 0, v[154:155]
	s_add_i32 m0, s59, 0x2000
	s_nop 0
	global_load_lds_dwordx4 v[228:229], off
	v_lshl_add_u64 v[228:229], s[48:49], 0, v[150:151]
	s_mov_b32 m0, s43
	s_nop 0
	global_load_lds_dwordx4 v[228:229], off
	s_mov_b32 m0, s51
	s_nop 0
	global_load_lds_dwordx4 v[230:231], off
	s_waitcnt vmcnt(8)
	s_waitcnt lgkmcnt(0)
	s_barrier
	s_setprio 1
	s_waitcnt lgkmcnt(0)
	v_mfma_f32_16x16x32_bf16 v[78:81], v[26:29], v[190:193], v[78:81]
	v_mfma_f32_16x16x32_bf16 v[74:77], v[42:45], v[190:193], v[74:77]
	v_mfma_f32_16x16x32_bf16 v[62:65], v[26:29], v[204:207], v[62:65]
	v_mfma_f32_16x16x32_bf16 v[58:61], v[42:45], v[204:207], v[58:61]
	v_mfma_f32_16x16x32_bf16 v[38:41], v[26:29], v[212:215], v[38:41]
	v_mfma_f32_16x16x32_bf16 v[34:37], v[42:45], v[212:215], v[34:37]
	v_mfma_f32_16x16x32_bf16 v[14:17], v[26:29], v[220:223], v[14:17]
	v_mfma_f32_16x16x32_bf16 v[10:13], v[42:45], v[220:223], v[10:13]
	v_mfma_f32_16x16x32_bf16 v[78:81], v[30:33], v[194:197], v[78:81]
	v_mfma_f32_16x16x32_bf16 v[74:77], v[46:49], v[194:197], v[74:77]
	v_mfma_f32_16x16x32_bf16 v[62:65], v[30:33], v[208:211], v[62:65]
	v_mfma_f32_16x16x32_bf16 v[58:61], v[46:49], v[208:211], v[58:61]
	v_mfma_f32_16x16x32_bf16 v[38:41], v[30:33], v[216:219], v[38:41]
	v_mfma_f32_16x16x32_bf16 v[34:37], v[46:49], v[216:219], v[34:37]
	v_mfma_f32_16x16x32_bf16 v[14:17], v[30:33], v[224:227], v[14:17]
	v_mfma_f32_16x16x32_bf16 v[10:13], v[46:49], v[224:227], v[10:13]
	s_setprio 0
	s_setprio 1
	v_mfma_f32_16x16x32_bf16 v[22:25], v[166:169], v[212:215], v[22:25]
	v_mfma_f32_16x16x32_bf16 v[18:21], v[182:185], v[212:215], v[18:21]
	v_mfma_f32_16x16x32_bf16 v[6:9], v[166:169], v[220:223], v[6:9]
	v_mfma_f32_16x16x32_bf16 v[2:5], v[182:185], v[220:223], v[2:5]
	v_mfma_f32_16x16x32_bf16 v[26:29], v[166:169], v[190:193], v[70:73]
	v_mfma_f32_16x16x32_bf16 v[30:33], v[182:185], v[190:193], v[66:69]
	v_mfma_f32_16x16x32_bf16 v[42:45], v[166:169], v[204:207], v[54:57]
	v_mfma_f32_16x16x32_bf16 v[46:49], v[182:185], v[204:207], v[50:53]
	v_mfma_f32_16x16x32_bf16 v[22:25], v[178:181], v[216:219], v[22:25]
	v_mfma_f32_16x16x32_bf16 v[18:21], v[186:189], v[216:219], v[18:21]
	v_mfma_f32_16x16x32_bf16 v[6:9], v[178:181], v[224:227], v[6:9]
	v_mfma_f32_16x16x32_bf16 v[2:5], v[186:189], v[224:227], v[2:5]
	v_mfma_f32_16x16x32_bf16 v[26:29], v[178:181], v[194:197], v[26:29]
	v_mfma_f32_16x16x32_bf16 v[30:33], v[186:189], v[194:197], v[30:33]
	v_mfma_f32_16x16x32_bf16 v[42:45], v[178:181], v[208:211], v[42:45]
	v_mfma_f32_16x16x32_bf16 v[46:49], v[186:189], v[208:211], v[46:49]
	s_setprio 0
	s_barrier
	s_add_i32 s59, 0, 0x18000
	s_add_i32 s60, 0, 0x1c000
	v_add_u32_e32 v70, s59, v163
	v_add_u32_e32 v186, s60, v163
	ds_read_b128 v[50:53], v70
	ds_read_b128 v[54:57], v70 offset:1024
	ds_read_b128 v[66:69], v70 offset:2048
	ds_read_b128 v[70:73], v70 offset:3072
	ds_read_b128 v[166:169], v186
	ds_read_b128 v[178:181], v186 offset:1024
	ds_read_b128 v[182:185], v186 offset:2048
	ds_read_b128 v[186:189], v186 offset:3072
	s_add_u32 s48, s48, 0x80000
	s_addc_u32 s49, s49, 0
	s_mov_b32 m0, s52
	v_lshl_add_u64 v[232:233], s[48:49], 0, v[150:151]
	ds_read_b128 v[190:193], v165 offset:32768
	ds_read_b128 v[194:197], v165 offset:33792
	ds_read_b128 v[204:207], v165 offset:34816
	ds_read_b128 v[208:211], v165 offset:35840
	ds_read_b128 v[212:215], v165 offset:36864
	ds_read_b128 v[216:219], v165 offset:37888
	ds_read_b128 v[220:223], v165 offset:38912
	ds_read_b128 v[224:227], v165 offset:39936
	global_load_lds_dwordx4 v[232:233], off
	v_lshl_add_u64 v[232:233], s[48:49], 0, v[152:153]
	s_mov_b32 m0, s53
	s_nop 0
	global_load_lds_dwordx4 v[232:233], off
	s_waitcnt vmcnt(8)
	s_waitcnt lgkmcnt(0)
	s_barrier
	s_setprio 1
	s_waitcnt lgkmcnt(0)
	v_mfma_f32_16x16x32_bf16 v[146:149], v[50:53], v[190:193], v[146:149]
	v_mfma_f32_16x16x32_bf16 v[142:145], v[66:69], v[190:193], v[142:145]
	v_mfma_f32_16x16x32_bf16 v[130:133], v[50:53], v[204:207], v[130:133]
	v_mfma_f32_16x16x32_bf16 v[126:129], v[66:69], v[204:207], v[126:129]
	v_mfma_f32_16x16x32_bf16 v[114:117], v[50:53], v[212:215], v[114:117]
	v_mfma_f32_16x16x32_bf16 v[110:113], v[66:69], v[212:215], v[110:113]
	v_mfma_f32_16x16x32_bf16 v[94:97], v[50:53], v[220:223], v[94:97]
	v_mfma_f32_16x16x32_bf16 v[90:93], v[66:69], v[220:223], v[90:93]
	v_mfma_f32_16x16x32_bf16 v[146:149], v[54:57], v[194:197], v[146:149]
	v_mfma_f32_16x16x32_bf16 v[142:145], v[70:73], v[194:197], v[142:145]
	v_mfma_f32_16x16x32_bf16 v[130:133], v[54:57], v[208:211], v[130:133]
	v_mfma_f32_16x16x32_bf16 v[126:129], v[70:73], v[208:211], v[126:129]
	v_mfma_f32_16x16x32_bf16 v[114:117], v[54:57], v[216:219], v[114:117]
	v_mfma_f32_16x16x32_bf16 v[110:113], v[70:73], v[216:219], v[110:113]
	v_mfma_f32_16x16x32_bf16 v[94:97], v[54:57], v[224:227], v[94:97]
	v_mfma_f32_16x16x32_bf16 v[90:93], v[70:73], v[224:227], v[90:93]
	s_setprio 0
	s_setprio 1
	v_mfma_f32_16x16x32_bf16 v[138:141], v[166:169], v[190:193], v[138:141]
	v_mfma_f32_16x16x32_bf16 v[134:137], v[182:185], v[190:193], v[134:137]
	v_mfma_f32_16x16x32_bf16 v[122:125], v[166:169], v[204:207], v[122:125]
	v_mfma_f32_16x16x32_bf16 v[118:121], v[182:185], v[204:207], v[118:121]
	v_mfma_f32_16x16x32_bf16 v[106:109], v[166:169], v[212:215], v[106:109]
	v_mfma_f32_16x16x32_bf16 v[102:105], v[182:185], v[212:215], v[102:105]
	v_mfma_f32_16x16x32_bf16 v[86:89], v[166:169], v[220:223], v[86:89]
	v_mfma_f32_16x16x32_bf16 v[82:85], v[182:185], v[220:223], v[82:85]
	v_mfma_f32_16x16x32_bf16 v[138:141], v[178:181], v[194:197], v[138:141]
	v_mfma_f32_16x16x32_bf16 v[134:137], v[186:189], v[194:197], v[134:137]
	v_mfma_f32_16x16x32_bf16 v[122:125], v[178:181], v[208:211], v[122:125]
	v_mfma_f32_16x16x32_bf16 v[118:121], v[186:189], v[208:211], v[118:121]
	v_mfma_f32_16x16x32_bf16 v[106:109], v[178:181], v[216:219], v[106:109]
	v_mfma_f32_16x16x32_bf16 v[102:105], v[186:189], v[216:219], v[102:105]
	v_mfma_f32_16x16x32_bf16 v[86:89], v[178:181], v[224:227], v[86:89]
	v_mfma_f32_16x16x32_bf16 v[82:85], v[186:189], v[224:227], v[82:85]
	s_setprio 0
	s_barrier
	s_add_i32 s48, s59, s50
	v_lshl_add_u64 v[160:161], v[160:161], 0, s[84:85]
	s_mov_b32 m0, s48
	ds_read_b128 v[190:193], v165 offset:49152
	ds_read_b128 v[194:197], v165 offset:50176
	ds_read_b128 v[204:207], v165 offset:51200
	ds_read_b128 v[208:211], v165 offset:52224
	ds_read_b128 v[212:215], v165 offset:53248
	ds_read_b128 v[216:219], v165 offset:54272
	ds_read_b128 v[220:223], v165 offset:55296
	ds_read_b128 v[224:227], v165 offset:56320
	global_load_lds_dwordx4 v[160:161], off
	s_add_i32 m0, s48, 0x2000
	s_add_u32 s46, s46, 0x80080
	v_lshl_add_u64 v[160:161], v[198:199], 0, s[84:85]
	s_addc_u32 s47, s47, 0
	s_add_i32 s48, s60, s50
	global_load_lds_dwordx4 v[160:161], off
	v_lshl_add_u64 v[160:161], s[46:47], 0, v[172:173]
	s_mov_b32 m0, s48
	s_nop 0
	global_load_lds_dwordx4 v[160:161], off
	v_lshl_add_u64 v[160:161], s[46:47], 0, v[154:155]
	s_add_i32 m0, s48, 0x2000
	s_nop 0
	global_load_lds_dwordx4 v[160:161], off
	v_lshl_add_u64 v[160:161], v[228:229], 0, s[84:85]
	s_mov_b32 m0, s54
	s_nop 0
	global_load_lds_dwordx4 v[160:161], off
	v_lshl_add_u64 v[160:161], v[230:231], 0, s[84:85]
	s_mov_b32 m0, s55
	s_nop 0
	global_load_lds_dwordx4 v[160:161], off
	s_waitcnt vmcnt(8)
	s_waitcnt lgkmcnt(0)
	s_barrier
	s_setprio 1
	s_waitcnt lgkmcnt(0)
	v_mfma_f32_16x16x32_bf16 v[78:81], v[50:53], v[190:193], v[78:81]
	v_mfma_f32_16x16x32_bf16 v[74:77], v[66:69], v[190:193], v[74:77]
	v_mfma_f32_16x16x32_bf16 v[62:65], v[50:53], v[204:207], v[62:65]
	v_mfma_f32_16x16x32_bf16 v[58:61], v[66:69], v[204:207], v[58:61]
	v_mfma_f32_16x16x32_bf16 v[38:41], v[50:53], v[212:215], v[38:41]
	v_mfma_f32_16x16x32_bf16 v[34:37], v[66:69], v[212:215], v[34:37]
	v_mfma_f32_16x16x32_bf16 v[14:17], v[50:53], v[220:223], v[14:17]
	v_mfma_f32_16x16x32_bf16 v[10:13], v[66:69], v[220:223], v[10:13]
	v_mfma_f32_16x16x32_bf16 v[78:81], v[54:57], v[194:197], v[78:81]
	v_mfma_f32_16x16x32_bf16 v[74:77], v[70:73], v[194:197], v[74:77]
	v_mfma_f32_16x16x32_bf16 v[62:65], v[54:57], v[208:211], v[62:65]
	v_mfma_f32_16x16x32_bf16 v[58:61], v[70:73], v[208:211], v[58:61]
	v_mfma_f32_16x16x32_bf16 v[38:41], v[54:57], v[216:219], v[38:41]
	v_mfma_f32_16x16x32_bf16 v[34:37], v[70:73], v[216:219], v[34:37]
	v_mfma_f32_16x16x32_bf16 v[14:17], v[54:57], v[224:227], v[14:17]
	v_mfma_f32_16x16x32_bf16 v[10:13], v[70:73], v[224:227], v[10:13]
	s_setprio 0
	s_setprio 1
	v_mfma_f32_16x16x32_bf16 v[26:29], v[166:169], v[190:193], v[26:29]
	v_mfma_f32_16x16x32_bf16 v[70:73], v[178:181], v[194:197], v[26:29]
	v_mfma_f32_16x16x32_bf16 v[26:29], v[182:185], v[190:193], v[30:33]
	v_mfma_f32_16x16x32_bf16 v[66:69], v[186:189], v[194:197], v[26:29]
	v_mfma_f32_16x16x32_bf16 v[26:29], v[166:169], v[204:207], v[42:45]
	v_mfma_f32_16x16x32_bf16 v[54:57], v[178:181], v[208:211], v[26:29]
	v_mfma_f32_16x16x32_bf16 v[26:29], v[182:185], v[204:207], v[46:49]
	v_mfma_f32_16x16x32_bf16 v[22:25], v[166:169], v[212:215], v[22:25]
	v_mfma_f32_16x16x32_bf16 v[18:21], v[182:185], v[212:215], v[18:21]
	v_mfma_f32_16x16x32_bf16 v[6:9], v[166:169], v[220:223], v[6:9]
	v_mfma_f32_16x16x32_bf16 v[2:5], v[182:185], v[220:223], v[2:5]
	v_mfma_f32_16x16x32_bf16 v[50:53], v[186:189], v[208:211], v[26:29]
	v_mfma_f32_16x16x32_bf16 v[22:25], v[178:181], v[216:219], v[22:25]
	v_mfma_f32_16x16x32_bf16 v[18:21], v[186:189], v[216:219], v[18:21]
	v_mfma_f32_16x16x32_bf16 v[6:9], v[178:181], v[224:227], v[6:9]
	v_mfma_f32_16x16x32_bf16 v[2:5], v[186:189], v[224:227], v[2:5]
	s_setprio 0
	s_barrier
	s_add_i32 s58, s58, 2
	s_add_u32 s44, s44, 0x100
	s_addc_u32 s45, s45, 0
	s_add_u32 s29, s29, 0x100
	s_addc_u32 s57, s57, 0
	s_cmp_gt_u32 s58, 29
	s_cbranch_scc0 .LBB0_258
	s_cmp_lt_i32 s42, 16
	s_cselect_b32 s19, 0, 16
	v_lshl_or_b32 v160, s42, 8, v164
	v_add_u32_e32 v26, s19, v160
	v_ashrrev_i32_e32 v27, 31, v26
	v_lshl_add_u64 v[26:27], v[26:27], 2, s[10:11]
	flat_load_dwordx4 v[46:49], v[26:27]
	flat_load_dwordx4 v[42:45], v[26:27] offset:16
	flat_load_dwordx4 v[30:33], v[26:27] offset:512
	s_nop 0
	flat_load_dwordx4 v[26:29], v[26:27] offset:528
	s_and_b64 vcc, exec, s[14:15]
	s_cbranch_vccz .LBB0_261
	s_barrier
.LBB0_261:
	s_and_b32 s19, s42, -4
	s_cmp_eq_u32 s19, 4
	s_cselect_b64 s[20:21], -1, 0
	s_cmp_eq_u32 s19, 16
	s_cselect_b64 s[44:45], -1, 0
	s_or_b64 s[20:21], s[20:21], s[44:45]
	s_cmp_eq_u32 s19, 28
	s_cselect_b64 s[44:45], -1, 0
	s_or_b64 s[20:21], s[44:45], s[20:21]
	s_cmp_eq_u32 s19, 24
	s_cselect_b64 s[44:45], -1, 0
	s_cmp_gt_i32 s42, 31
	s_cselect_b64 s[46:47], -1, 0
	s_or_b64 s[44:45], s[46:47], s[44:45]
	s_cmp_lt_i32 s42, 16
	s_cselect_b32 s19, 0, 16
	v_lshl_or_b32 v160, s42, 8, v164
	v_cndmask_b32_e64 v161, 0, 1, s[20:21]
	s_and_b64 s[20:21], s[44:45], exec
	v_readfirstlane_b32 s19, v161
	s_cselect_b32 s23, 2, s19
	s_cmp_gt_i32 s23, 1
	s_mov_b64 s[20:21], -1
	s_waitcnt vmcnt(0) lgkmcnt(0)
	v_pk_add_f32 v[148:149], v[148:149], v[48:49]
	v_pk_add_f32 v[146:147], v[146:147], v[46:47]
	v_pk_add_f32 v[144:145], v[144:145], v[44:45]
	v_pk_add_f32 v[142:143], v[142:143], v[42:43]
	s_cbranch_scc0 .LBB0_263
	v_mul_f32_e32 v166, 0xbfb8aa3b, v147
	v_mul_f32_e32 v167, 0xbfb8aa3b, v148
	v_exp_f32_e32 v166, v166
	v_exp_f32_e32 v168, v167
	v_mul_f32_e32 v167, 0xbfb8aa3b, v149
	v_exp_f32_e32 v169, v167
	v_add_f32_e32 v166, 1.0, v166
	v_rcp_f32_e32 v167, v166
	v_add_f32_e32 v166, 1.0, v168
	v_add_f32_e32 v168, 1.0, v169
	v_mul_f32_e32 v169, 0xbfb8aa3b, v142
	v_exp_f32_e32 v178, v169
	v_mul_f32_e32 v169, 0xbfb8aa3b, v143
	v_exp_f32_e32 v179, v169
	v_rcp_f32_e32 v169, v168
	v_add_f32_e32 v168, 1.0, v178
	v_mul_f32_e32 v161, 0xbfb8aa3b, v146
	v_add_f32_e32 v178, 1.0, v179
	v_mul_f32_e32 v179, 0xbfb8aa3b, v144
	v_exp_f32_e32 v180, v179
	v_mul_f32_e32 v179, 0xbfb8aa3b, v145
	v_exp_f32_e32 v161, v161
	v_exp_f32_e32 v181, v179
	v_rcp_f32_e32 v179, v178
	v_add_f32_e32 v178, 1.0, v180
	v_add_f32_e32 v161, 1.0, v161
	v_add_f32_e32 v180, 1.0, v181
	v_rcp_f32_e32 v161, v161
	v_rcp_f32_e32 v166, v166
	v_rcp_f32_e32 v168, v168
	v_rcp_f32_e32 v178, v178
	v_rcp_f32_e32 v180, v180
	s_mov_b64 s[20:21], 0
